# dilated units: chunk index rotated by the round so every workgroup sees all chunk positions (XCD balance)
# speedup vs baseline: 1.0197x; 1.0041x over previous
; template <int MODE>
; DI void flash_loop(char* smem, const bf16_t* Kbase, size_t ldk, const bf16_t* Vtbase, size_t ldv, ull tiles, ull wtiles,
;                    const bf16x8 (&qf)[4], f32x16 (&o)[2], float& m, float& l, int tq, int tqmin, int tqmax, int maxdist, const float* cn_lds, ull lmask) {
;     ...
;   auto issue = [&](int kt, u32x4 (&rk)[2], u32x4 (&rv)[2]) {
; #pragma unroll
;     for (int q = 0; q < 2; ++q) { rk[q] = *(const u32x4*)(Kbase + (size_t)(64 * kt + lr + 32 * q) * ldk + c8); rv[q] = *(const u32x4*)(Vtbase + (size_t)(lr + 32 * q) * ldv + 64 * kt + c8); }
;   };
;   auto stash = [&](int stage, const u32x4 (&rk)[2], const u32x4 (&rv)[2]) {
;     bf16_t* Ks = (bf16_t*)(smem + stage * (2 * 64 * LSTR * 2)); bf16_t* Vs = Ks + 64 * LSTR;
; #pragma unroll
;     for (int q = 0; q < 2; ++q) { *(u32x4*)(Ks + (lr + 32 * q) * LSTR + c8) = rk[q]; *(u32x4*)(Vs + (lr + 32 * q) * LSTR + c8) = rv[q]; }
;   };
;   auto next_tile = [&]() -> int { if (!tiles) return -1; const int t = __builtin_ctzll(tiles); tiles &= tiles - 1; return t; };
;   auto compute = [&](int kt, int stage) {
;     if (!((wtiles >> kt) & 1ull)) return;
;     const bf16_t* Ks = (const bf16_t*)(smem + stage * (2 * 64 * LSTR * 2)); const bf16_t* Vs = Ks + 64 * LSTR;
;     const bool sel = ((lmask >> kt) & 1ull) != 0;
;     const bool interior = (64 * kt + 63 <= tqmin) && (MODE != 0 || (tqmax - 64 * kt <= maxdist));
;     int hm = 3;
; DI void dil_unit(const Params& p, int gi, int dlog, int u, char* smem, bool probe = false) {
;   const int tid = otid(), lane = tid & 63, w = __builtin_amdgcn_readfirstlane(tid >> 6), r = lane & 31, h = lane >> 5;
;   const int L = SEQ >> dlog, nch = L >> 5;
;   const int chunk = u % nch, kvh = (u / nch) & 3, bq = u / (nch * 4);
;   const int q0 = chunk * 32, head = kvh * 4 + w, tq = q0 + r; const size_t row = (size_t)bq * L + tq;
;   __syncthreads();
;   bf16_t* Qg = p.Q + (size_t)gi * NTOK * 1024;
;   bf16x8 qf[4]; load_q(Qg + row * 1024 + head * 64, qf);
;   f32x16 o[2]; zero_o(o);
;   float m = -1e30f, l = 0.f;
;   int lo = (q0 - 128) >> 6; lo = lo < 0 ? 0 : lo; const int hi = (q0 + 31) >> 6;
;   const ull tiles = tile_range(lo, hi);
;   flash_loop<0>(smem, p.Kb + (size_t)gi * NTOK * 256 + (size_t)bq * L * 256 + kvh * 64, 256, p.Vt + (size_t)gi * NTOK * 256 + (size_t)(bq * 4 + kvh) * 64 * L, L, tiles, tiles, qf, o, m, l, tq, q0, q0 + 31, 128, nullptr, 0ull);
.LBB0_914:
	s_ashr_i32 s2, s1, 12
	v_mov_b32_e32 v156, v167
	s_lshl_b32 s3, s2, 1
	s_and_b32 s4, s1, 0xfff
	v_readfirstlane_b32 s5, v156
	s_ashr_i32 s7, s5, 6
	s_lshr_b32 s5, 0x80, s3
	s_add_i32 s5, s5, -1
	s_and_b32 s29, s5, s4
	s_lshr_b32 s100, s4, 9
	s_add_i32 s29, s29, s100
	s_and_b32 s29, s29, s5
	s_sub_i32 s5, 7, s3
	s_lshr_b32 s5, s4, s5
	s_lshr_b32 s10, 0x1000, s3
	s_and_b32 s6, s5, 3
	s_sub_i32 s3, 9, s3
	s_lshr_b32 s11, s4, s3
	s_lshl_b32 s3, s6, 2
	s_lshl_b32 s5, s29, 5
	s_add_i32 s4, s7, s3
	s_ashr_i32 s3, s2, 31
	v_readlane_b32 s12, v229, 29
	v_and_or_b32 v157, v156, 31, s5
	s_mul_i32 s58, s11, s10
	s_lshl_b64 s[8:9], s[2:3], 26
	v_readlane_b32 s24, v229, 41
	v_add_u32_e32 v146, s58, v157
	v_mov_b32_e32 v147, v1
	v_readlane_b32 s25, v229, 42
	s_add_u32 s8, s24, s8
	s_addc_u32 s9, s25, s9
	v_lshlrev_b64 v[2:3], 11, v[146:147]
	v_lshl_add_u64 v[2:3], s[8:9], 0, v[2:3]
	s_lshl_b32 s8, s4, 6
	s_ashr_i32 s9, s8, 31
	v_lshl_add_u64 v[148:149], s[8:9], 1, v[2:3]
	s_lshr_b32 s8, s29, 1
	s_add_i32 s28, s5, 0xffffff80
	s_add_i32 s8, s8, 1
	s_ashr_i32 s7, s28, 6
	s_lshl_b64 s[8:9], -1, s8
	s_max_i32 s7, s7, 0
	s_not_b64 s[8:9], s[8:9]
	s_cmpk_lt_u32 s29, 0x7e
	s_cselect_b32 s9, s9, -1
	s_cselect_b32 s8, s8, -1
	s_lshl_b64 s[30:31], -1, s7
	s_and_b64 s[8:9], s[30:31], s[8:9]
	v_readlane_b32 s26, v229, 43
	v_readlane_b32 s27, v229, 44
	s_cmp_eq_u64 s[8:9], 0
	s_barrier
	v_readlane_b32 s13, v229, 30
	v_readlane_b32 s14, v229, 31
	v_readlane_b32 s15, v229, 32
	v_readlane_b32 s16, v229, 33
	v_readlane_b32 s17, v229, 34
	v_readlane_b32 s18, v229, 35
	v_readlane_b32 s19, v229, 36
	v_readlane_b32 s20, v229, 37
	v_readlane_b32 s21, v229, 38
	v_readlane_b32 s22, v229, 39
	v_readlane_b32 s23, v229, 40
	s_cbranch_scc1 .LBB0_917
	s_lshl_b64 s[30:31], s[2:3], 24
	s_add_u32 s7, s26, s30
	s_addc_u32 s29, s27, s31
	s_lshl_b64 s[36:37], s[58:59], 9
	s_add_u32 s7, s7, s36
	s_addc_u32 s29, s29, s37
	s_lshl_b32 s33, s6, 6
	s_lshl_b32 s6, s6, 7
	s_add_u32 s6, s7, s6
	s_addc_u32 s7, s29, 0
	v_readlane_b32 s12, v230, 51
	v_readlane_b32 s13, v230, 52
	s_add_u32 s29, s12, s30
	s_addc_u32 s36, s13, s31
	s_lshl_b32 s11, s11, 8
	s_or_b32 s11, s33, s11
	s_mul_i32 s58, s11, s10
	s_lshl_b64 s[30:31], s[58:59], 1
	s_add_u32 s30, s29, s30
	s_addc_u32 s31, s36, s31
	s_add_u32 s36, s8, -1
	s_ff1_i32_b64 s33, s[8:9]
	v_lshlrev_b32_e32 v0, 1, v166
	s_addc_u32 s37, s9, -1
	s_lshl_b32 s11, s33, 6
	v_lshl_add_u64 v[2:3], v[148:149], 0, v[0:1]
	v_add_lshl_u32 v0, s11, v169, 9
	global_load_dwordx4 v[98:101], v[2:3], off
	global_load_dwordx4 v[102:105], v[2:3], off offset:32
	global_load_dwordx4 v[106:109], v[2:3], off offset:64
	global_load_dwordx4 v[110:113], v[2:3], off offset:96
	v_lshl_add_u64 v[2:3], s[6:7], 0, v[0:1]
	v_lshlrev_b32_e32 v0, 1, v168
	v_lshl_add_u64 v[2:3], v[2:3], 0, v[0:1]
	global_load_dwordx4 v[114:117], v[2:3], off
	v_mul_u32_u24_e32 v2, s10, v169
	v_lshlrev_b32_e32 v2, 1, v2
	v_mov_b32_e32 v3, v1
	v_lshl_add_u64 v[2:3], s[30:31], 0, v[2:3]
	s_lshl_b32 s58, s33, 7
	v_lshl_add_u64 v[4:5], v[2:3], 0, s[58:59]
	v_lshl_add_u64 v[4:5], v[4:5], 0, v[0:1]
	global_load_dwordx4 v[118:121], v[4:5], off
	v_add_lshl_u32 v4, s11, v171, 9
	v_mov_b32_e32 v5, v1
	v_lshl_add_u64 v[4:5], s[6:7], 0, v[4:5]
	v_lshl_add_u64 v[4:5], v[4:5], 0, v[0:1]
	s_lshl_b32 s10, s10, 6
	s_mov_b32 s11, s59
	global_load_dwordx4 v[122:125], v[4:5], off
	v_lshl_add_u64 v[4:5], v[2:3], 0, s[10:11]
	v_lshl_add_u64 v[6:7], v[4:5], 0, s[58:59]
	v_lshl_add_u64 v[6:7], v[6:7], 0, v[0:1]
	global_load_dwordx4 v[126:129], v[6:7], off
	s_and_b64 s[10:11], s[36:37], s[8:9]
	s_ff1_i32_b64 s29, s[10:11]
	s_cmp_lg_u64 s[10:11], 0
	s_cselect_b32 s67, s29, -1
	s_cmp_lt_i32 s67, 0
	v_readlane_b32 s14, v230, 53
	v_readlane_b32 s15, v230, 54
	v_readlane_b32 s16, v230, 55
	v_readlane_b32 s17, v230, 56
	v_readlane_b32 s18, v230, 57
	v_readlane_b32 s19, v230, 58
	v_readlane_b32 s20, v230, 59
	v_readlane_b32 s21, v230, 60
	v_readlane_b32 s22, v230, 61
	v_readlane_b32 s23, v230, 62
	v_readlane_b32 s24, v230, 63
	v_readlane_b32 s25, v229, 0
	v_readlane_b32 s26, v229, 1
	v_readlane_b32 s27, v229, 2
	s_cbranch_scc1 .LBB0_918
	s_lshl_b32 s29, s67, 6
	v_add_u32_e32 v6, s29, v169
	v_mov_b32_e32 v7, v1
	v_lshlrev_b64 v[6:7], 9, v[6:7]
	v_lshl_add_u64 v[6:7], s[6:7], 0, v[6:7]
	v_lshl_add_u64 v[6:7], v[6:7], 0, v[0:1]
	s_lshl_b32 s58, s67, 7
	global_load_dwordx4 v[130:133], v[6:7], off
	v_lshl_add_u64 v[6:7], v[2:3], 0, s[58:59]
	v_lshl_add_u64 v[6:7], v[6:7], 0, v[0:1]
	global_load_dwordx4 v[134:137], v[6:7], off
	v_add_u32_e32 v6, s29, v171
	v_mov_b32_e32 v7, v1
	v_lshlrev_b64 v[6:7], 9, v[6:7]
	v_lshl_add_u64 v[6:7], s[6:7], 0, v[6:7]
	v_lshl_add_u64 v[6:7], v[6:7], 0, v[0:1]
	global_load_dwordx4 v[138:141], v[6:7], off
	v_lshl_add_u64 v[6:7], v[4:5], 0, s[58:59]
	v_lshl_add_u64 v[6:7], v[6:7], 0, v[0:1]
	global_load_dwordx4 v[142:145], v[6:7], off
	s_branch .LBB0_919
